# m1 chunk-state stores: MFMA operands swapped (C^T layout) so 16 two-byte stores per wave and chunk become 4 dwordx2 stores
# baseline (speedup 1.0000x reference)
.LBB0_292:
	s_lshl_b32 s91, s29, 8
	s_add_u32 s91, s91, 0x1a000
	v_add_u32_e32 v191, s91, v208
	ds_read_b128 v[72:75], v191 offset:18432
	ds_read_b128 v[76:79], v191 offset:18448
	ds_read_b128 v[84:87], v191 offset:2048
	ds_read_b128 v[88:91], v191 offset:2064
	ds_read_b128 v[96:99], v191 offset:6144
	ds_read_b128 v[100:103], v191 offset:6160
	ds_read_b128 v[108:111], v191 offset:10240
	ds_read_b128 v[112:115], v191 offset:10256
	ds_read_b128 v[120:123], v191 offset:14336
	ds_read_b128 v[124:127], v191 offset:14352
	v_lshrrev_b32_e32 v8, 3, v15
	v_and_b32_e32 v16, 7, v15
	v_lshlrev_b32_e32 v16, 3, v16
	v_mul_u32_u24_e32 v24, 0x90, v8
	v_lshl_add_u32 v24, v16, 1, v24
	s_waitcnt vmcnt(0)
	ds_write_b128 v24, v[44:47] offset:9216
	ds_write_b128 v24, v[48:51] offset:18432
	v_cmp_gt_i32_e32 vcc, s66, v15
	s_and_saveexec_b64 s[4:5], vcc
	v_cmp_gt_u32_e32 vcc, 8, v15
	s_nop 1
	v_cndmask_b32_e32 v2, 0, v205, vcc
	v_mov_b32_e32 v3, v2
	v_mov_b32_e32 v4, v2
	v_mov_b32_e32 v5, v2
	ds_write_b128 v24, v[2:5] offset:27648
	s_or_b64 exec, exec, s[4:5]
	s_waitcnt lgkmcnt(0)
	v_mov_b32_e32 v4, v72
	v_mov_b32_e32 v5, v73
	v_mov_b32_e32 v6, v74
	v_mov_b32_e32 v7, v75
	v_mov_b32_e32 v0, v76
	v_mov_b32_e32 v1, v77
	v_mov_b32_e32 v2, v78
	v_mov_b32_e32 v3, v79
	s_and_saveexec_b64 s[4:5], s[46:47]
	v_lshlrev_b32_e32 v32, 16, v80
	v_and_b32_e32 v33, 0xffff0000, v80
	v_pk_fma_f32 v[4:5], v[84:85], v[32:33], v[4:5]
	v_lshlrev_b32_e32 v34, 16, v81
	v_and_b32_e32 v35, 0xffff0000, v81
	v_pk_fma_f32 v[6:7], v[86:87], v[34:35], v[6:7]
	v_lshlrev_b32_e32 v32, 16, v82
	v_and_b32_e32 v33, 0xffff0000, v82
	v_pk_fma_f32 v[0:1], v[88:89], v[32:33], v[0:1]
	v_lshlrev_b32_e32 v34, 16, v83
	v_and_b32_e32 v35, 0xffff0000, v83
	v_pk_fma_f32 v[2:3], v[90:91], v[34:35], v[2:3]
	s_or_b64 exec, exec, s[4:5]
	s_and_saveexec_b64 s[4:5], s[48:49]
	v_lshlrev_b32_e32 v32, 16, v92
	v_and_b32_e32 v33, 0xffff0000, v92
	v_pk_fma_f32 v[4:5], v[96:97], v[32:33], v[4:5]
	v_lshlrev_b32_e32 v34, 16, v93
	v_and_b32_e32 v35, 0xffff0000, v93
	v_pk_fma_f32 v[6:7], v[98:99], v[34:35], v[6:7]
	v_lshlrev_b32_e32 v32, 16, v94
	v_and_b32_e32 v33, 0xffff0000, v94
	v_pk_fma_f32 v[0:1], v[100:101], v[32:33], v[0:1]
	v_lshlrev_b32_e32 v34, 16, v95
	v_and_b32_e32 v35, 0xffff0000, v95
	v_pk_fma_f32 v[2:3], v[102:103], v[34:35], v[2:3]
	s_or_b64 exec, exec, s[4:5]
	s_and_saveexec_b64 s[4:5], s[50:51]
	v_lshlrev_b32_e32 v32, 16, v104
	v_and_b32_e32 v33, 0xffff0000, v104
	v_pk_fma_f32 v[4:5], v[108:109], v[32:33], v[4:5]
	v_lshlrev_b32_e32 v34, 16, v105
	v_and_b32_e32 v35, 0xffff0000, v105
	v_pk_fma_f32 v[6:7], v[110:111], v[34:35], v[6:7]
	v_lshlrev_b32_e32 v32, 16, v106
	v_and_b32_e32 v33, 0xffff0000, v106
	v_pk_fma_f32 v[0:1], v[112:113], v[32:33], v[0:1]
	v_lshlrev_b32_e32 v34, 16, v107
	v_and_b32_e32 v35, 0xffff0000, v107
	v_pk_fma_f32 v[2:3], v[114:115], v[34:35], v[2:3]
	s_or_b64 exec, exec, s[4:5]
	v_lshlrev_b32_e32 v32, 16, v116
	v_and_b32_e32 v33, 0xffff0000, v116
	v_pk_fma_f32 v[4:5], v[120:121], v[32:33], v[4:5]
	v_lshlrev_b32_e32 v34, 16, v117
	v_and_b32_e32 v35, 0xffff0000, v117
	v_pk_fma_f32 v[6:7], v[122:123], v[34:35], v[6:7]
	v_lshlrev_b32_e32 v32, 16, v118
	v_and_b32_e32 v33, 0xffff0000, v118
	v_pk_fma_f32 v[0:1], v[124:125], v[32:33], v[0:1]
	v_lshlrev_b32_e32 v34, 16, v119
	v_and_b32_e32 v35, 0xffff0000, v119
	v_pk_fma_f32 v[2:3], v[126:127], v[34:35], v[2:3]
	s_waitcnt vmcnt(0)
	v_mul_f32_e32 v11, 0xbfb8aa3b, v4
	v_exp_f32_e32 v11, v11
	s_waitcnt lgkmcnt(0)
	s_barrier
	v_add_f32_e32 v11, 1.0, v11
	v_rcp_f32_e32 v11, v11
	s_movk_i32 s19, 0x7fff
	v_and_b32_e32 v9, 15, v15
	s_lshr_b32 s4, s27, 2
	v_mul_f32_e32 v4, v4, v11
	v_mul_f32_e32 v11, 0xbfb8aa3b, v5
	v_exp_f32_e32 v11, v11
	v_lshrrev_b32_e32 v10, 4, v14
	v_lshlrev_b32_e32 v24, 2, v10
	v_add_f32_e32 v11, 1.0, v11
	v_rcp_f32_e32 v11, v11
	s_nop 0
	v_mul_f32_e32 v5, v5, v11
	v_mul_f32_e32 v11, 0xbfb8aa3b, v6
	v_exp_f32_e32 v11, v11
	s_nop 0
	v_add_f32_e32 v11, 1.0, v11
	v_rcp_f32_e32 v11, v11
	s_nop 0
	v_mul_f32_e32 v6, v6, v11
	v_mul_f32_e32 v11, 0xbfb8aa3b, v7
	v_exp_f32_e32 v11, v11
	s_nop 0
	v_add_f32_e32 v11, 1.0, v11
	v_rcp_f32_e32 v11, v11
	s_nop 0
	v_mul_f32_e32 v7, v7, v11
	v_mul_f32_e32 v11, 0xbfb8aa3b, v0
	v_exp_f32_e32 v11, v11
	s_nop 0
	v_add_f32_e32 v11, 1.0, v11
	v_rcp_f32_e32 v11, v11
	s_nop 0
	v_mul_f32_e32 v0, v0, v11
	v_mul_f32_e32 v11, 0xbfb8aa3b, v1
	v_exp_f32_e32 v11, v11
	s_nop 0
	v_add_f32_e32 v11, 1.0, v11
	v_rcp_f32_e32 v11, v11
	s_nop 0
	v_mul_f32_e32 v1, v1, v11
	v_mul_f32_e32 v11, 0xbfb8aa3b, v2
	v_exp_f32_e32 v11, v11
	s_nop 0
	v_add_f32_e32 v11, 1.0, v11
	v_rcp_f32_e32 v11, v11
	s_nop 0
	v_mul_f32_e32 v2, v2, v11
	v_mul_f32_e32 v11, 0xbfb8aa3b, v3
	v_exp_f32_e32 v11, v11
	s_nop 0
	v_add_f32_e32 v11, 1.0, v11
	v_rcp_f32_e32 v11, v11
	s_nop 0
	v_mul_f32_e32 v3, v3, v11
	v_lshl_add_u32 v11, v8, 2, 0
	ds_read_b32 v12, v11 offset:29952
	v_lshlrev_b32_e32 v8, 1, v8
	v_sub_u32_e32 v8, v11, v8
	v_lshlrev_b32_e32 v13, 1, v16
	v_xor_b32_e32 v8, v8, v13
	v_mad_u32_u24 v8, v16, s84, v8
	s_waitcnt lgkmcnt(0)
	v_mul_f32_e32 v4, v12, v4
	v_bfe_u32 v11, v4, 16, 1
	v_add3_u32 v4, v4, v11, s19
	ds_write_b16_d16_hi v8, v4
	v_mul_f32_e32 v4, v12, v5
	v_bfe_u32 v5, v4, 16, 1
	v_add3_u32 v4, v4, v5, s19
	ds_write_b16_d16_hi v8, v4 offset:144
	v_mul_f32_e32 v4, v12, v6
	v_bfe_u32 v5, v4, 16, 1
	v_add3_u32 v4, v4, v5, s19
	ds_write_b16_d16_hi v8, v4 offset:288
	v_mul_f32_e32 v4, v12, v7
	v_bfe_u32 v5, v4, 16, 1
	v_add3_u32 v4, v4, v5, s19
	v_mul_f32_e32 v0, v12, v0
	ds_write_b16_d16_hi v8, v4 offset:432
	v_bfe_u32 v4, v0, 16, 1
	v_add3_u32 v0, v0, v4, s19
	ds_write_b16_d16_hi v8, v0 offset:576
	v_mul_f32_e32 v0, v12, v1
	v_bfe_u32 v1, v0, 16, 1
	v_add3_u32 v0, v0, v1, s19
	ds_write_b16_d16_hi v8, v0 offset:720
	v_mul_f32_e32 v0, v12, v2
	v_bfe_u32 v1, v0, 16, 1
	v_add3_u32 v0, v0, v1, s19
	ds_write_b16_d16_hi v8, v0 offset:864
	v_mul_f32_e32 v0, v12, v3
	v_bfe_u32 v1, v0, 16, 1
	v_add3_u32 v0, v0, v1, s19
	v_and_or_b32 v11, s4, 48, v9
	s_ashr_i32 s4, s27, 2
	ds_write_b16_d16_hi v8, v0 offset:1008
	v_and_b32_e32 v0, 48, v14
	s_andn2_b32 s4, s4, 63
	v_add_u32_e32 v8, 0, v0
	v_or_b32_e32 v0, s4, v9
	v_mad_u64_u32 v[12:13], s[6:7], v0, s84, v[8:9]
	s_waitcnt lgkmcnt(0)
	s_barrier
	v_lshrrev_b32_e32 v32, 3, v11
	v_and_b32_e32 v32, 7, v32
	v_lshlrev_b32_e32 v32, 4, v32
	v_xor_b32_e32 v32, v8, v32
	v_mad_u32_u24 v15, v11, s84, v32
	v_xor_b32_e32 v32, 64, v32
	v_mad_u32_u24 v33, v11, s84, v32
	v_and_b32_e32 v34, 48, v11
	v_or_b32_e32 v34, v34, v24
	s_mov_b32 s90, 0x7060302
	ds_read_b128 v[4:7], v12 offset:9216
	ds_read_b128 v[0:3], v15
	s_waitcnt lgkmcnt(0)
	v_mfma_f32_16x16x32_bf16 v[16:19], v[0:3], v[4:7], 0
	ds_read_b128 v[20:23], v12 offset:9280
	ds_read_b128 v[4:7], v33
	v_or_b32_e32 v12, s4, v9
	v_lshl_or_b32 v12, v12, 6, v34
	s_waitcnt lgkmcnt(0)
	v_mfma_f32_16x16x32_bf16 v[16:19], v[4:7], v[20:23], v[16:19]
	s_or_b32 s5, s4, 16
	s_nop 6
	v_ashrrev_i32_e32 v13, 31, v12
	v_lshl_add_u64 v[12:13], v[12:13], 1, s[16:17]
	v_bfe_u32 v35, v16, 16, 1
	v_bfe_u32 v36, v17, 16, 1
	v_bfe_u32 v37, v18, 16, 1
	v_bfe_u32 v38, v19, 16, 1
	v_add3_u32 v35, v16, v35, s19
	v_add3_u32 v36, v17, v36, s19
	v_add3_u32 v37, v18, v37, s19
	v_add3_u32 v38, v19, v38, s19
	v_perm_b32 v36, v36, v35, s90
	v_perm_b32 v37, v38, v37, s90
	global_store_dwordx2 v[12:13], v[36:37], off
	v_or_b32_e32 v12, s5, v9
	v_mad_u64_u32 v[12:13], s[6:7], v12, s84, v[8:9]
	ds_read_b128 v[16:19], v12 offset:9216
	ds_read_b128 v[20:23], v12 offset:9280
	s_waitcnt lgkmcnt(1)
	v_mfma_f32_16x16x32_bf16 v[16:19], v[0:3], v[16:19], 0
	v_or_b32_e32 v12, s5, v9
	v_lshl_or_b32 v12, v12, 6, v34
	s_or_b32 s5, s4, 32
	s_waitcnt lgkmcnt(0)
	v_mfma_f32_16x16x32_bf16 v[16:19], v[4:7], v[20:23], v[16:19]
	s_nop 7
	v_ashrrev_i32_e32 v13, 31, v12
	v_lshl_add_u64 v[12:13], v[12:13], 1, s[16:17]
	v_bfe_u32 v35, v16, 16, 1
	v_bfe_u32 v36, v17, 16, 1
	v_bfe_u32 v37, v18, 16, 1
	v_bfe_u32 v38, v19, 16, 1
	v_add3_u32 v35, v16, v35, s19
	v_add3_u32 v36, v17, v36, s19
	v_add3_u32 v37, v18, v37, s19
	v_add3_u32 v38, v19, v38, s19
	v_perm_b32 v36, v36, v35, s90
	v_perm_b32 v37, v38, v37, s90
	global_store_dwordx2 v[12:13], v[36:37], off
	v_or_b32_e32 v12, s5, v9
	v_mad_u64_u32 v[12:13], s[6:7], v12, s84, v[8:9]
	ds_read_b128 v[16:19], v12 offset:9216
	ds_read_b128 v[20:23], v12 offset:9280
	s_waitcnt lgkmcnt(1)
	v_mfma_f32_16x16x32_bf16 v[16:19], v[0:3], v[16:19], 0
	v_or_b32_e32 v12, s5, v9
	v_lshl_or_b32 v12, v12, 6, v34
	s_or_b32 s6, s4, 48
	s_waitcnt lgkmcnt(0)
	v_mfma_f32_16x16x32_bf16 v[16:19], v[4:7], v[20:23], v[16:19]
	s_cmpk_gt_u32 s27, 0xff
	s_nop 6
	v_ashrrev_i32_e32 v13, 31, v12
	v_lshl_add_u64 v[12:13], v[12:13], 1, s[16:17]
	v_bfe_u32 v35, v16, 16, 1
	v_bfe_u32 v36, v17, 16, 1
	v_bfe_u32 v37, v18, 16, 1
	v_bfe_u32 v38, v19, 16, 1
	v_add3_u32 v35, v16, v35, s19
	v_add3_u32 v36, v17, v36, s19
	v_add3_u32 v37, v18, v37, s19
	v_add3_u32 v38, v19, v38, s19
	v_perm_b32 v36, v36, v35, s90
	v_perm_b32 v37, v38, v37, s90
	global_store_dwordx2 v[12:13], v[36:37], off
	v_or_b32_e32 v12, s6, v9
	v_mad_u64_u32 v[12:13], s[4:5], v12, s84, v[8:9]
	ds_read_b128 v[16:19], v12 offset:9216
	ds_read_b128 v[20:23], v12 offset:9280
	s_waitcnt lgkmcnt(1)
	v_mfma_f32_16x16x32_bf16 v[16:19], v[0:3], v[16:19], 0
	v_or_b32_e32 v8, s6, v9
	s_waitcnt lgkmcnt(0)
	v_mfma_f32_16x16x32_bf16 v[16:19], v[4:7], v[20:23], v[16:19]
	s_nop 7
	v_lshl_or_b32 v12, v8, 6, v34
	v_ashrrev_i32_e32 v13, 31, v12
	v_lshl_add_u64 v[12:13], v[12:13], 1, s[16:17]
	v_bfe_u32 v35, v16, 16, 1
	v_bfe_u32 v36, v17, 16, 1
	v_bfe_u32 v37, v18, 16, 1
	v_bfe_u32 v38, v19, 16, 1
	v_add3_u32 v35, v16, v35, s19
	v_add3_u32 v36, v17, v36, s19
	v_add3_u32 v37, v18, v37, s19
	v_add3_u32 v38, v19, v38, s19
	v_perm_b32 v36, v36, v35, s90
	v_perm_b32 v37, v38, v37, s90
	global_store_dwordx2 v[12:13], v[36:37], off
	s_cbranch_scc1 .LBB0_287
	v_lshlrev_b32_e32 v8, 3, v10
	v_mul_u32_u24_e32 v9, 0x90, v9
	v_lshlrev_b32_e32 v8, 1, v8
	v_add3_u32 v8, 0, v9, v8
	ds_read_b128 v[16:19], v8 offset:27648
	v_cmp_gt_u32_e32 vcc, 16, v14
	s_waitcnt lgkmcnt(0)
	v_mfma_f32_16x16x32_bf16 v[0:3], v[16:19], v[0:3], 0
	ds_read_b128 v[16:19], v8 offset:27712
	s_waitcnt lgkmcnt(0)
	v_mfma_f32_16x16x32_bf16 v[0:3], v[16:19], v[4:7], v[0:3]
	s_and_saveexec_b64 s[4:5], vcc
	s_cbranch_execz .LBB0_286
	s_nop 5
	v_bfe_u32 v1, v0, 16, 1
	s_movk_i32 s6, 0x7fff
	v_add3_u32 v2, v0, v1, s6
	v_lshlrev_b32_e32 v0, 1, v11
	v_mov_b32_e32 v1, v172
	v_lshl_add_u64 v[0:1], s[16:17], 0, v[0:1]
	v_add_co_u32_e32 v0, vcc, 0x4000, v0
	s_nop 1
	v_addc_co_u32_e32 v1, vcc, 0, v1, vcc
	global_store_short_d16_hi v[0:1], v2, off
	s_branch .LBB0_286
